# GEMM k-loop preheader: conservative vmcnt(0) relaxed to vmcnt(6) so next-tile staging loads and last epilogue stores stay in flight
# baseline (speedup 1.0000x reference)
; template <class Epi>
; __device__ __forceinline__ void gemm_phase(LAS unsigned char* lds, const Gemm g, const StaticOrder& S, const Epi& E, int wid_s) {
;     ...
;     if (!has_next) break;
; #pragma unroll
;     for (int a = 0; a < 2; ++a)
; #pragma unroll
;       for (int b = 0; b < 2; ++b)
; #pragma unroll
;         for (int m = 0; m < 4; ++m)
; #pragma unroll
;           for (int n = 0; n < 2; ++n) acc[a][b][m][n] = (f32x4){0.f, 0.f, 0.f, 0.f};
;     cur = nxt; cA = nA; cB = nB; ++ui;
.LBB0_423:
	v_readlane_b32 s4, v254, 54
	v_readlane_b32 s5, v254, 55
	s_andn2_b64 vcc, exec, s[4:5]
	s_cbranch_vccnz .LBB0_426
	s_add_u32 s4, s8, 0x80
	s_addc_u32 s5, s9, 0
	s_add_u32 s8, s6, 0x100
	v_mov_b32_e32 v2, 0
	s_addc_u32 s9, s7, 0
	s_mov_b32 s6, 0
	v_mov_b32_e32 v3, v2
	v_mov_b32_e32 v4, v2
	v_mov_b32_e32 v5, v2
	v_mov_b32_e32 v6, v2
	v_mov_b32_e32 v7, v2
	v_mov_b32_e32 v8, v2
	v_mov_b32_e32 v9, v2
	v_mov_b32_e32 v18, v2
	v_mov_b32_e32 v19, v2
	v_mov_b32_e32 v20, v2
	v_mov_b32_e32 v21, v2
	v_mov_b32_e32 v22, v2
	v_mov_b32_e32 v23, v2
	v_mov_b32_e32 v24, v2
	v_mov_b32_e32 v25, v2
	v_mov_b32_e32 v34, v2
	v_mov_b32_e32 v35, v2
	s_waitcnt vmcnt(6)
	v_mov_b32_e32 v36, v2
	v_mov_b32_e32 v37, v2
	v_mov_b32_e32 v38, v2
	v_mov_b32_e32 v39, v2
	v_mov_b32_e32 v40, v2
	v_mov_b32_e32 v41, v2
	v_mov_b32_e32 v50, v2
	v_mov_b32_e32 v51, v2
	v_mov_b32_e32 v52, v2
	v_mov_b32_e32 v53, v2
	v_mov_b32_e32 v54, v2
	v_mov_b32_e32 v55, v2
	v_mov_b32_e32 v56, v2
	v_mov_b32_e32 v57, v2
	v_mov_b32_e32 v10, v2
	v_mov_b32_e32 v11, v2
	v_mov_b32_e32 v12, v2
	v_mov_b32_e32 v13, v2
	v_mov_b32_e32 v14, v2
	v_mov_b32_e32 v15, v2
	v_mov_b32_e32 v16, v2
	v_mov_b32_e32 v17, v2
	v_mov_b32_e32 v26, v2
	v_mov_b32_e32 v27, v2
	v_mov_b32_e32 v28, v2
	v_mov_b32_e32 v29, v2
	v_mov_b32_e32 v30, v2
	v_mov_b32_e32 v31, v2
	v_mov_b32_e32 v32, v2
	v_mov_b32_e32 v33, v2
	v_mov_b32_e32 v42, v2
	v_mov_b32_e32 v43, v2
	v_mov_b32_e32 v44, v2
	v_mov_b32_e32 v45, v2
	v_mov_b32_e32 v46, v2
	v_mov_b32_e32 v47, v2
	v_mov_b32_e32 v48, v2
	v_mov_b32_e32 v49, v2
	v_mov_b32_e32 v58, v2
	v_mov_b32_e32 v59, v2
	v_mov_b32_e32 v60, v2
	v_mov_b32_e32 v61, v2
	v_mov_b32_e32 v62, v2
	v_mov_b32_e32 v63, v2
	v_mov_b32_e32 v64, v2
	v_mov_b32_e32 v65, v2
	v_mov_b32_e32 v66, v2
	v_mov_b32_e32 v67, v2
	v_mov_b32_e32 v68, v2
	v_mov_b32_e32 v69, v2
	v_mov_b32_e32 v70, v2
	v_mov_b32_e32 v71, v2
	v_mov_b32_e32 v72, v2
	v_mov_b32_e32 v73, v2
	v_mov_b32_e32 v82, v2
	v_mov_b32_e32 v83, v2
	v_mov_b32_e32 v84, v2
	v_mov_b32_e32 v85, v2
	v_mov_b32_e32 v86, v2
	v_mov_b32_e32 v87, v2
	v_mov_b32_e32 v88, v2
	v_mov_b32_e32 v89, v2
	v_mov_b32_e32 v98, v2
	v_mov_b32_e32 v99, v2
	v_mov_b32_e32 v100, v2
	v_mov_b32_e32 v101, v2
	v_mov_b32_e32 v102, v2
	v_mov_b32_e32 v103, v2
	v_mov_b32_e32 v104, v2
	v_mov_b32_e32 v105, v2
	v_mov_b32_e32 v114, v2
	v_mov_b32_e32 v115, v2
	v_mov_b32_e32 v116, v2
	v_mov_b32_e32 v117, v2
	v_mov_b32_e32 v118, v2
	v_mov_b32_e32 v119, v2
	v_mov_b32_e32 v120, v2
	v_mov_b32_e32 v121, v2
	v_mov_b32_e32 v74, v2
	v_mov_b32_e32 v75, v2
	v_mov_b32_e32 v76, v2
	v_mov_b32_e32 v77, v2
	v_mov_b32_e32 v78, v2
	v_mov_b32_e32 v79, v2
	v_mov_b32_e32 v80, v2
	v_mov_b32_e32 v81, v2
	v_mov_b32_e32 v90, v2
	v_mov_b32_e32 v91, v2
	v_mov_b32_e32 v92, v2
	v_mov_b32_e32 v93, v2
	v_mov_b32_e32 v94, v2
	v_mov_b32_e32 v95, v2
	v_mov_b32_e32 v96, v2
	v_mov_b32_e32 v97, v2
	v_mov_b32_e32 v106, v2
	v_mov_b32_e32 v107, v2
	v_mov_b32_e32 v108, v2
	v_mov_b32_e32 v109, v2
	v_mov_b32_e32 v110, v2
	v_mov_b32_e32 v111, v2
	v_mov_b32_e32 v112, v2
	v_mov_b32_e32 v113, v2
	v_mov_b32_e32 v122, v2
	v_mov_b32_e32 v123, v2
	v_mov_b32_e32 v124, v2
	v_mov_b32_e32 v125, v2
	v_mov_b32_e32 v126, v2
	v_mov_b32_e32 v127, v2
	v_mov_b32_e32 v128, v2
	v_mov_b32_e32 v129, v2
